# prompt attention unit prologue: mask wait / invert / ds_write moved behind the issue of the first K/V LDS-DMAs and the Q loads (the two round trips overlap)
# speedup vs baseline: 1.0056x; 1.0056x over previous
.Lml_issued:
.LBB0_1900:
	s_lshl_b32 s56, s8, 8
	s_or_b32 s4, s20, s56
	s_lshl_b32 s5, s52, 5
	s_add_u32 s4, s4, s5
	s_addc_u32 s5, s21, 0
	s_and_b32 s53, s7, 0x3fffffc0
	s_lshl_b32 s22, s52, 4
	s_lshl_b32 s57, s52, 10
	s_cmp_lg_u32 0, -1
	s_cselect_b32 s8, 0, 0
	s_add_i32 s57, s57, s8
	s_add_i32 s59, s56, 0x100
	s_lshl_b64 s[4:5], s[4:5], 11
	v_and_or_b32 v2, s22, 48, v101
	s_add_u32 s40, s47, s4
	s_addc_u32 s41, s48, s5
	v_lshlrev_b32_e32 v2, 9, v2
	s_lshr_b32 s4, s7, 2
	v_lshl_add_u64 v[220:221], v[200:201], 0, s[22:23]
	v_lshl_add_u64 v[4:5], s[24:25], 0, v[2:3]
	s_and_b32 s22, s4, 0x3fffffc0
	s_waitcnt lgkmcnt(0)
	v_lshl_add_u64 v[4:5], v[4:5], 0, s[22:23]
	v_mov_b32_e32 v217, v3
	s_mov_b32 s4, m0
	s_mov_b32 m0, s57
	s_nop 0
	global_load_lds_dwordx4 v[220:221], off
	s_mov_b32 m0, s4
	v_lshl_add_u64 v[222:223], v[4:5], 0, v[216:217]
	s_add_i32 s58, s57, 0x6000
	s_mov_b32 s4, m0
	s_mov_b32 m0, s58
	s_nop 0
	global_load_lds_dwordx4 v[222:223], off
	s_mov_b32 m0, s4
	v_lshl_add_u64 v[4:5], v[220:221], 0, s[26:27]
	s_add_i32 s4, s57, 0x2000
	s_mov_b32 s5, m0
	s_mov_b32 m0, s4
	s_nop 0
	global_load_lds_dwordx4 v[4:5], off
	s_mov_b32 m0, s5
	v_lshl_add_u64 v[4:5], s[40:41], 0, v[202:203]
	v_mov_b32_e32 v219, v3
	v_lshl_add_u64 v[4:5], v[4:5], 0, v[218:219]
	global_load_dwordx4 v[130:133], v[4:5], off
	global_load_dwordx4 v[126:129], v[4:5], off offset:32
	global_load_dwordx4 v[122:125], v[4:5], off offset:64
	global_load_dwordx4 v[114:117], v[4:5], off offset:96
	v_lshl_add_u64 v[4:5], v[220:221], 0, s[28:29]
	s_add_i32 s4, s57, 0x4000
	s_mov_b32 s5, m0
	s_mov_b32 m0, s4
	s_nop 0
	global_load_lds_dwordx4 v[4:5], off
	s_mov_b32 m0, s5
	s_waitcnt vmcnt(8)
	v_not_b32_e32 v36, v36
	v_not_b32_e32 v37, v37
	v_not_b32_e32 v38, v38
	v_not_b32_e32 v39, v39
	v_add_u32_e32 v2, s6, v1
	ds_write_b128 v2, v[36:39]
	s_cmp_lt_u32 s56, 0x100
	s_cbranch_scc1 .Lml_done
	v_not_b32_e32 v40, v40
	v_not_b32_e32 v41, v41
	v_not_b32_e32 v42, v42
	v_not_b32_e32 v43, v43
	v_add_u32_e32 v2, s6, v228
	ds_write_b128 v2, v[40:43]
	s_cmp_lt_u32 s56, 0x200
	s_cbranch_scc1 .Lml_done
	v_not_b32_e32 v44, v44
	v_not_b32_e32 v45, v45
	v_not_b32_e32 v46, v46
	v_not_b32_e32 v47, v47
	v_add_u32_e32 v2, s6, v229
	ds_write_b128 v2, v[44:47]
	s_cmp_lt_u32 s56, 0x300
	s_cbranch_scc1 .Lml_done
	v_not_b32_e32 v48, v48
	v_not_b32_e32 v49, v49
	v_not_b32_e32 v50, v50
	v_not_b32_e32 v51, v51
	v_add_u32_e32 v2, s6, v230
	ds_write_b128 v2, v[48:51]
	s_cmp_lt_u32 s56, 0x400
	s_cbranch_scc1 .Lml_done
	v_not_b32_e32 v52, v52
	v_not_b32_e32 v53, v53
	v_not_b32_e32 v54, v54
	v_not_b32_e32 v55, v55
	v_add_u32_e32 v2, s6, v231
	ds_write_b128 v2, v[52:55]
	s_cmp_lt_u32 s56, 0x500
	s_cbranch_scc1 .Lml_done
	v_not_b32_e32 v56, v56
	v_not_b32_e32 v57, v57
	v_not_b32_e32 v58, v58
	v_not_b32_e32 v59, v59
	v_add_u32_e32 v2, s6, v232
	ds_write_b128 v2, v[56:59]
	s_cmp_lt_u32 s56, 0x600
	s_cbranch_scc1 .Lml_done
	v_not_b32_e32 v60, v60
	v_not_b32_e32 v61, v61
	v_not_b32_e32 v62, v62
	v_not_b32_e32 v63, v63
	v_add_u32_e32 v2, s6, v233
	ds_write_b128 v2, v[60:63]
	s_cmp_lt_u32 s56, 0x700
	s_cbranch_scc1 .Lml_done
	v_not_b32_e32 v64, v64
	v_not_b32_e32 v65, v65
	v_not_b32_e32 v66, v66
	v_not_b32_e32 v67, v67
	v_add_u32_e32 v2, s6, v234
	ds_write_b128 v2, v[64:67]
.Lml_done:
	s_waitcnt vmcnt(3) lgkmcnt(0)
	s_barrier
	ds_read_b128 v[4:7], v235
	ds_read_b128 v[20:23], v235 offset:512
	ds_read_b128 v[36:39], v235 offset:2048
	v_add3_u32 v209, s6, v249, v243
	s_lshl_b32 s22, s53, 2
	s_add_i32 s53, s22, 0
	s_mov_b32 s4, 0
	s_movk_i32 s60, 0x2000
	s_movk_i32 s62, 0x4000
	s_lshr_b32 s59, s59, 6
	s_mov_b32 s22, 1
	v_lshl_add_u32 v207, v100, 2, s53
	s_waitcnt vmcnt(3) lgkmcnt(2)
	v_mfma_f32_32x32x16_bf16 v[4:19], v[4:7], v[130:133], 0
	s_waitcnt vmcnt(2) lgkmcnt(0)
	v_mfma_f32_32x32x16_bf16 v[4:19], v[36:39], v[126:129], v[4:19]
	ds_read_b128 v[36:39], v235 offset:2560
	v_mfma_f32_32x32x16_bf16 v[20:35], v[20:23], v[130:133], 0
	s_waitcnt lgkmcnt(0)
	v_mfma_f32_32x32x16_bf16 v[20:35], v[36:39], v[126:129], v[20:35]
	ds_read_b128 v[36:39], v235 offset:4096
	ds_read_b128 v[40:43], v235 offset:4608
	s_waitcnt vmcnt(1) lgkmcnt(1)
	v_mfma_f32_32x32x16_bf16 v[4:19], v[36:39], v[122:125], v[4:19]
	ds_read_b128 v[36:39], v235 offset:6656
	ds_read_b128 v[44:47], v235 offset:6144
	s_waitcnt lgkmcnt(2)
	v_mfma_f32_32x32x16_bf16 v[20:35], v[40:43], v[122:125], v[20:35]
	s_waitcnt vmcnt(0) lgkmcnt(0)
	v_mfma_f32_32x32x16_bf16 v[4:19], v[44:47], v[114:117], v[4:19]
	v_mfma_f32_32x32x16_bf16 v[20:35], v[36:39], v[114:117], v[20:35]
	s_nop 15
	s_nop 7
	ds_read_b32 v2, v209
	s_waitcnt lgkmcnt(0)
	v_bfe_i32 v36, v2, 0, 1
	v_bfi_b32 v4, v36, s49, v4
	s_nop 0
	s_waitcnt vmcnt(0) lgkmcnt(0)
	s_barrier
	s_nop 0
	v_bfe_i32 v36, v2, 1, 1
	v_bfi_b32 v5, v36, s49, v5
	s_nop 0
	s_nop 0
	v_bfe_i32 v36, v2, 2, 1
	v_bfi_b32 v6, v36, s49, v6
	s_nop 0
	s_nop 0
	v_bfe_i32 v36, v2, 3, 1
	v_bfi_b32 v7, v36, s49, v7
	s_nop 0
	s_nop 0
	v_bfe_i32 v36, v2, 4, 1
	v_bfi_b32 v8, v36, s49, v8
	s_nop 0
	s_nop 0
	v_bfe_i32 v36, v2, 5, 1
	v_bfi_b32 v9, v36, s49, v9
	s_nop 0
	s_nop 0
	v_bfe_i32 v36, v2, 6, 1
	v_bfi_b32 v10, v36, s49, v10
	s_nop 0
	s_nop 0
	v_bfe_i32 v36, v2, 7, 1
	v_bfi_b32 v11, v36, s49, v11
	s_nop 0
	s_nop 0
	v_bfe_i32 v36, v2, 8, 1
	v_bfi_b32 v12, v36, s49, v12
	s_nop 0
	s_nop 0
	v_bfe_i32 v36, v2, 9, 1
	v_bfi_b32 v13, v36, s49, v13
	s_nop 0
	s_nop 0
	v_bfe_i32 v36, v2, 10, 1
	v_bfi_b32 v14, v36, s49, v14
	s_nop 0
	s_nop 0
	v_bfe_i32 v36, v2, 11, 1
	v_bfi_b32 v15, v36, s49, v15
	s_nop 0
	s_nop 0
	v_bfe_i32 v36, v2, 12, 1
	v_bfi_b32 v16, v36, s49, v16
	s_nop 0
	s_nop 0
	v_bfe_i32 v36, v2, 13, 1
	v_bfi_b32 v17, v36, s49, v17
	s_nop 0
	s_nop 0
	v_bfe_i32 v36, v2, 14, 1
	v_bfi_b32 v18, v36, s49, v18
	s_nop 0
	s_nop 0
	v_bfe_i32 v36, v2, 15, 1
	v_bfi_b32 v19, v36, s49, v19
	s_nop 0
	s_nop 0
	v_bfe_i32 v36, v2, 16, 1
	v_bfi_b32 v20, v36, s49, v20
	s_nop 0
	s_nop 0
	v_bfe_i32 v36, v2, 17, 1
	v_bfi_b32 v21, v36, s49, v21
	s_nop 0
	s_nop 0
	v_bfe_i32 v36, v2, 18, 1
	v_bfi_b32 v22, v36, s49, v22
	s_nop 0
	s_nop 0
	v_bfe_i32 v36, v2, 19, 1
	v_bfi_b32 v23, v36, s49, v23
	s_nop 0
	s_nop 0
	v_bfe_i32 v36, v2, 20, 1
	v_bfi_b32 v24, v36, s49, v24
	s_nop 0
	s_nop 0
	v_bfe_i32 v36, v2, 21, 1
	v_bfi_b32 v25, v36, s49, v25
	s_nop 0
	s_nop 0
	v_bfe_i32 v36, v2, 22, 1
	v_bfi_b32 v26, v36, s49, v26
	s_nop 0
	s_nop 0
	v_bfe_i32 v36, v2, 23, 1
	v_bfi_b32 v27, v36, s49, v27
	s_nop 0
	s_nop 0
	v_bfe_i32 v36, v2, 24, 1
	v_bfi_b32 v28, v36, s49, v28
	s_nop 0
	s_nop 0
	v_bfe_i32 v36, v2, 25, 1
	v_bfi_b32 v29, v36, s49, v29
	s_nop 0
	s_nop 0
	v_bfe_i32 v36, v2, 26, 1
	v_bfi_b32 v30, v36, s49, v30
	s_nop 0
	s_nop 0
	v_bfe_i32 v36, v2, 27, 1
	v_bfi_b32 v31, v36, s49, v31
	s_nop 0
	s_nop 0
	v_bfe_i32 v36, v2, 28, 1
	v_bfi_b32 v32, v36, s49, v32
	s_nop 0
	s_nop 0
	v_bfe_i32 v36, v2, 29, 1
	v_bfi_b32 v33, v36, s49, v33
	s_nop 0
	s_nop 0
	v_bfe_i32 v36, v2, 30, 1
	v_bfi_b32 v34, v36, s49, v34
	s_nop 0
	s_nop 0
	v_bfe_i32 v36, v2, 31, 1
	v_bfi_b32 v35, v36, s49, v35
	s_nop 0
	v_max3_f32 v2, v4, v5, v20
	s_nop 0
	v_max3_f32 v36, v6, v7, v21
	v_max3_f32 v2, v2, v22, v23
	s_nop 0
	v_max3_f32 v36, v36, v10, v11
	v_max3_f32 v2, v2, v8, v9
	s_nop 0
	v_max3_f32 v36, v36, v26, v27
	v_max3_f32 v2, v2, v24, v25
	s_nop 0
	v_max3_f32 v36, v36, v14, v15
	v_max3_f32 v2, v2, v12, v13
	s_nop 0
	v_max3_f32 v36, v36, v30, v31
	v_max3_f32 v2, v2, v28, v29
	s_nop 0
	v_max3_f32 v36, v36, v18, v19
	v_max3_f32 v2, v2, v16, v17
	s_nop 0
	v_max3_f32 v36, v36, v34, v35
	v_max3_f32 v2, v2, v32, v33
	s_nop 0
	v_max_f32_e32 v2, v2, v36
	s_nop 0
	v_mov_b32_e32 v36, v2
	s_nop 1
	v_permlane32_swap_b32_e32 v2, v36
	v_max_f32_e32 v2, v2, v36
	s_nop 0
	v_cmp_ngt_f32_e32 vcc, s50, v2
	s_nop 1
	v_cndmask_b32_e32 v2, 0, v2, vcc
	v_sub_f32_e32 v4, v4, v2
	v_sub_f32_e32 v5, v5, v2
	v_add_f32_e32 v211, v3, v2
	v_sub_f32_e32 v20, v20, v2
	v_sub_f32_e32 v21, v21, v2
	v_sub_f32_e32 v6, v6, v2
	s_nop 0
	v_exp_f32_e32 v52, v4
	v_exp_f32_e32 v53, v5
	v_lshl_add_u64 v[4:5], v[220:221], 0, s[30:31]
	s_mov_b32 s63, m0
	s_mov_b32 m0, s57
	s_nop 0
	global_load_lds_dwordx4 v[4:5], off
	s_mov_b32 m0, s63
	v_lshl_add_u64 v[4:5], v[222:223], 0, s[26:27]
	s_add_i32 s63, s57, 0x8000
	s_mov_b32 s64, m0
	s_mov_b32 m0, s63
	s_nop 0
	global_load_lds_dwordx4 v[4:5], off
	s_mov_b32 m0, s64
	ds_read_b128 v[162:165], v235 offset:8192
	ds_read_b128 v[158:161], v235 offset:8704
	ds_read_b128 v[154:157], v235 offset:10240
	ds_read_b128 v[150:153], v235 offset:10752
	ds_read_b128 v[146:149], v235 offset:12288
	ds_read_b128 v[142:145], v235 offset:12800
	ds_read_b128 v[138:141], v235 offset:14336
	ds_read_b128 v[134:137], v235 offset:14848
	v_sub_f32_e32 v22, v22, v2
	v_sub_f32_e32 v7, v7, v2
	v_sub_f32_e32 v23, v23, v2
	v_sub_f32_e32 v8, v8, v2
	v_sub_f32_e32 v24, v24, v2
	v_sub_f32_e32 v9, v9, v2
	v_sub_f32_e32 v25, v25, v2
	v_sub_f32_e32 v10, v10, v2
	v_sub_f32_e32 v26, v26, v2
	v_sub_f32_e32 v11, v11, v2
	v_sub_f32_e32 v27, v27, v2
	v_sub_f32_e32 v12, v12, v2
	v_sub_f32_e32 v28, v28, v2
	v_sub_f32_e32 v13, v13, v2
	v_sub_f32_e32 v29, v29, v2
	v_sub_f32_e32 v14, v14, v2
	v_sub_f32_e32 v30, v30, v2
	v_sub_f32_e32 v15, v15, v2
	v_sub_f32_e32 v31, v31, v2
	v_sub_f32_e32 v16, v16, v2
	v_sub_f32_e32 v32, v32, v2
	v_sub_f32_e32 v17, v17, v2
	v_sub_f32_e32 v33, v33, v2
	v_sub_f32_e32 v18, v18, v2
	v_sub_f32_e32 v34, v34, v2
	v_sub_f32_e32 v19, v19, v2
	v_sub_f32_e32 v2, v35, v2
	v_exp_f32_e32 v54, v6
	v_exp_f32_e32 v55, v7
	v_exp_f32_e32 v56, v8
	v_exp_f32_e32 v57, v9
	v_exp_f32_e32 v58, v10
	v_exp_f32_e32 v59, v11
	v_exp_f32_e32 v60, v12
	v_exp_f32_e32 v61, v13
	v_exp_f32_e32 v62, v14
	v_exp_f32_e32 v63, v15
	v_exp_f32_e32 v64, v16
	v_exp_f32_e32 v65, v17
	v_exp_f32_e32 v66, v18
	v_exp_f32_e32 v67, v19
	v_exp_f32_e32 v36, v20
	v_exp_f32_e32 v37, v21
	v_exp_f32_e32 v38, v22
	v_exp_f32_e32 v39, v23
	v_exp_f32_e32 v40, v24
	v_exp_f32_e32 v41, v25
	v_exp_f32_e32 v42, v26
	v_exp_f32_e32 v43, v27
	v_exp_f32_e32 v44, v28
	v_exp_f32_e32 v45, v29
	v_exp_f32_e32 v46, v30
	v_exp_f32_e32 v47, v31
	v_exp_f32_e32 v48, v32
	v_exp_f32_e32 v49, v33
	v_exp_f32_e32 v50, v34
	v_exp_f32_e32 v51, v2
	s_waitcnt vmcnt(2) lgkmcnt(0)
	s_barrier
	s_andn2_b64 vcc, exec, s[42:43]
	s_cbranch_vccnz .LBB0_1962
	v_mov_b32_e32 v16, v3
	v_mov_b32_e32 v17, v3
	v_mov_b32_e32 v2, v3
	v_mov_b32_e32 v4, v3
	v_mov_b32_e32 v5, v3
	v_mov_b32_e32 v6, v3
	v_mov_b32_e32 v7, v3
	v_mov_b32_e32 v8, v3
	v_mov_b32_e32 v9, v3
	v_mov_b32_e32 v10, v3
	v_mov_b32_e32 v11, v3
	v_mov_b32_e32 v12, v3
	v_mov_b32_e32 v13, v3
	v_mov_b32_e32 v14, v3
	v_mov_b32_e32 v15, v3
	v_mov_b64_e32 v[34:35], v[16:17]
	v_mov_b64_e32 v[32:33], v[14:15]
	v_mov_b64_e32 v[30:31], v[12:13]
	v_mov_b64_e32 v[28:29], v[10:11]
	v_mov_b64_e32 v[26:27], v[8:9]
	v_mov_b64_e32 v[24:25], v[6:7]
	v_mov_b64_e32 v[22:23], v[4:5]
	v_mov_b64_e32 v[20:21], v[2:3]
	v_mov_b64_e32 v[18:19], v[16:17]
	v_add_u32_e32 v182, s61, v244
	s_mov_b32 s8, 0
	s_movk_i32 s4, 0x4000
	s_movk_i32 s12, 0x2000
	v_mov_b32_e32 v213, 0
	s_mov_b32 s5, 6
	s_mov_b64 s[6:7], 0
	v_mov_b64_e32 v[16:17], v[14:15]
	v_mov_b64_e32 v[14:15], v[12:13]
	v_mov_b64_e32 v[12:13], v[10:11]
	v_mov_b64_e32 v[10:11], v[8:9]
	v_mov_b64_e32 v[8:9], v[6:7]
	v_mov_b64_e32 v[6:7], v[4:5]
	v_mov_b64_e32 v[4:5], v[2:3]
